# MLA attention loop as uniform MFMA/VALU interleave in every wave (instead of the wave role split), other edits as v170
# speedup vs baseline: 1.0080x; 1.0076x over previous
; #define LAS __attribute__((address_space(3)))
; template <int GRP> __device__ __forceinline__ void att_stk(const AttCtx<GRP>& C, int buf, const u32x4& kreg, const u32x4& preg) {
;     *(LAS u32x4*)(C.lds + buf * KBUF + C.kwo) = kreg; if (GRP == 0 && C.tid < 256) *(LAS u32x4*)(C.lds + buf * KBUF + C.pwo) = preg;
; }
; template <int GRP> __device__ __forceinline__ void att_stld(const AttCtx<GRP>& C, int s, u32x4& kreg, u32x4& preg, u32x4& vreg) {
;     constexpr int NSTEP = 256;
;     if (s + 2 < NSTEP) att_stk<GRP>(C, s & 1, kreg, preg);
;     if (s + 1 < NSTEP) att_stv<GRP>(C, (s + 1) & 1, vreg);
;     if (s + 3 < NSTEP) att_ldk<GRP>(C, s + 3, kreg, preg);
;     if (s + 2 < NSTEP) att_ldv<GRP>(C, s + 2, vreg);
; }
; template <int GRP, int KS0, int N> __device__ __forceinline__ void att_kfrag(const AttCtx<GRP>& C, int slot, bf16x8 (&kf)[2 * N]) {
;     const LAS unsigned char* kb = C.lds + slot * KBUF + C.kro;
; #pragma unroll
;     for (int i = 0; i < N; ++i) { kf[2 * i] = *(const LAS bf16x8*)(kb + (KS0 + i) * 32); kf[2 * i + 1] = *(const LAS bf16x8*)(kb + 32 * KST + (KS0 + i) * 32); }
; template <int GRP, bool has_next> __device__ __forceinline__ void att_step(const AttCtx<GRP>& C, AttState<GRP>& S, int s, f32x16& P0, f32x16& P1, f32x16& PN0, f32x16& PN1, u32x4& kreg, u32x4& preg, u32x4& vreg) {
;     ...
;         att_kfrag<GRP, 0, NK0>(C, (s + 1) & 1, kfa);
;     }
;     if (has_next) { PN0 = __builtin_amdgcn_mfma_f32_32x32x16_bf16(kfa[0], S.qr[0], (f32x16){}, 0, 0, 0); PN1 = __builtin_amdgcn_mfma_f32_32x32x16_bf16(kfa[1], S.qr[0], (f32x16){}, 0, 0, 0); }
;     if ((t & 7) == 0) {
;         float ma = max3f(P0[0], P0[1], P0[2]), mb = max3f(P0[3], P0[4], P0[5]), mc = max3f(P1[0], P1[1], P1[2]), md = max3f(P1[3], P1[4], P1[5]);
;         ma = max3f(ma, P0[6], P0[7]); mb = max3f(mb, P0[8], P0[9]); mc = max3f(mc, P1[6], P1[7]); md = max3f(md, P1[8], P1[9]);
;         ma = max3f(ma, P0[10], P0[11]); mb = max3f(mb, P0[12], P0[13]); mc = max3f(mc, P1[10], P1[11]); md = max3f(md, P1[12], P1[13]);
;         ma = max3f(ma, P0[14], P0[15]); mc = max3f(mc, P1[14], P1[15]); ma = max3f(ma, mb, mc); mb = md;
;         const float mx = xhalf_max(max2f(ma, mb));
;         const int up = __any(mx > THR), dn = (t == 0) ? __any(mx < -THR) : 0;
.LBB0_776:
	ds_read_b128 v[136:139], v174 offset:13312
	ds_read_b128 v[140:143], v174 offset:19968
	ds_read_b128 v[144:147], v174 offset:13344
	ds_read_b128 v[148:151], v174 offset:20000
	s_and_b32 s10, s69, 6
	s_waitcnt lgkmcnt(3)
	v_mfma_f32_32x32x16_bf16 v[80:95], v[136:139], v[128:131], 0
	ds_read_b128 v[176:179], v174 offset:13376
	s_waitcnt lgkmcnt(3)
	v_mfma_f32_32x32x16_bf16 v[64:79], v[140:143], v[128:131], 0
	ds_read_b128 v[180:183], v174 offset:20032
	s_waitcnt vmcnt(1)
	ds_write_b128 v171, v[104:107]
	s_and_saveexec_b64 s[82:83], s[6:7]
	ds_write_b128 v172, v[100:103] offset:128
	s_or_b64 exec, exec, s[82:83]
	s_mov_b32 s84, 0xfe000000
	s_mov_b32 s85, -1
	s_waitcnt vmcnt(0)
	ds_write_b128 v169, v[132:135] offset:35840
	v_lshl_add_u64 v[192:193], v[166:167], 0, s[84:85]
	s_add_i32 s14, s67, 0xfffff800
	s_and_b32 s14, s14, 0x1f800
	s_lshl_b32 s62, s14, 1
	global_load_dwordx4 v[104:107], v[192:193], off
	s_and_saveexec_b64 s[82:83], s[6:7]
	v_lshl_add_u64 v[190:191], v[160:161], 0, s[62:63]
	global_load_dwordx4 v[100:103], v[190:191], off
	s_or_b64 exec, exec, s[82:83]
	s_mov_b32 s84, 0xffffe000
	s_nop 0
	v_lshl_add_u64 v[192:193], v[166:167], 0, s[84:85]
	global_load_dwordx4 v[132:135], v[192:193], off
	s_cmp_lg_u32 s10, 0
	s_cbranch_scc1 .Lmla_e_main
	v_max3_f32 v96, v48, v49, v50
	v_max3_f32 v99, v32, v33, v34
	v_max3_f32 v98, v51, v52, v53
	v_max3_f32 v252, v35, v36, v37
	s_and_b32 s14, s69, 56
	v_max3_f32 v96, v96, v54, v55
	v_max3_f32 v99, v99, v38, v39
	v_max3_f32 v98, v98, v56, v57
	v_max3_f32 v252, v252, v40, v41
	s_cmp_eq_u32 s14, 0
	v_max3_f32 v96, v96, v58, v59
	v_max3_f32 v99, v99, v42, v43
	v_max3_f32 v98, v98, v60, v61
	v_max3_f32 v252, v252, v44, v45
	s_cselect_b64 s[10:11], -1, 0
	v_max3_f32 v96, v96, v62, v63
	v_max3_f32 v99, v99, v46, v47
	s_cmp_lg_u32 s14, 0
	v_max3_f32 v96, v96, v98, v99
	s_nop 0
	v_max_f32_e32 v96, v96, v252
	s_nop 0
	v_mov_b32_e32 v98, v96
	s_nop 1
	v_permlane32_swap_b32_e32 v96, v98
	v_max_f32_e32 v98, v98, v98
	v_max_f32_e32 v96, v96, v96
	v_max_f32_e32 v96, v96, v98
	v_cmp_lt_f32_e32 vcc, s54, v96
	v_mov_b32_e32 v98, 0
	s_cbranch_scc1 .Lmla_mx1
	v_cmp_gt_f32_e64 s[14:15], s55, v96
	s_cmp_lg_u64 s[14:15], 0
	s_cselect_b64 s[14:15], -1, 0
	v_cndmask_b32_e64 v98, 0, 1, s[14:15]

; #define ATT_SUMPACK(j) do { const float e0_ = (j) < 8 ? P0[2 * ((j) & 7)] : P1[2 * ((j) & 7)], e1_ = (j) < 8 ? P0[2 * ((j) & 7) + 1] : P1[2 * ((j) & 7) + 1]; \
;         if ((j) & 1) { rc += e0_; rd += e1_; } else { ra += e0_; rb += e1_; } S.pw[j] = cvtpk(e0_, e1_); } while (0)
; template <int GRP, bool has_next> __device__ __forceinline__ void att_step(const AttCtx<GRP>& C, AttState<GRP>& S, int s, f32x16& P0, f32x16& P1, f32x16& PN0, f32x16& PN1, u32x4& kreg, u32x4& preg, u32x4& vreg) {
;     ...
;     constexpr int NE = NKS - 1;
;     float ra = 0.f, rb = 0.f, rc = 0.f, rd = 0.f;
;     ...
; #pragma unroll
;     for (int c = 1; c < NKS; ++c) {
;         if (has_next) {
;             if (c == NK0) att_kfrag<GRP, NK0, NK1>(C, (s + 1) & 1, kfb);
;             const bf16x8 a0 = c < NK0 ? kfa[2 * c] : kfb[2 * (c - NK0)], a1 = c < NK0 ? kfa[2 * c + 1] : kfb[2 * (c - NK0) + 1];
;             PN0 = __builtin_amdgcn_mfma_f32_32x32x16_bf16(a0, S.qr[c], PN0, 0, 0, 0); PN1 = __builtin_amdgcn_mfma_f32_32x32x16_bf16(a1, S.qr[c], PN1, 0, 0, 0);
;         }
; #pragma unroll
;         for (int j = (c - 1) * 16 / NE; j < c * 16 / NE; ++j) {
;             if (j < 8) { P0[2 * j] = __builtin_amdgcn_exp2f(P0[2 * j]); P0[2 * j + 1] = __builtin_amdgcn_exp2f(P0[2 * j + 1]); }
;             else { P1[2 * (j - 8)] = __builtin_amdgcn_exp2f(P1[2 * (j - 8)]); P1[2 * (j - 8) + 1] = __builtin_amdgcn_exp2f(P1[2 * (j - 8) + 1]); }
;         }
;         if (c > 1) {
; #pragma unroll
;             for (int j = (c - 2) * 16 / NE; j < (c - 1) * 16 / NE; ++j) ATT_SUMPACK(j);
;         }
;         __builtin_amdgcn_sched_barrier(0);
;     }
;     if (has_next && S.refnz && t != 63) { PN0 = __builtin_amdgcn_mfma_f32_32x32x16_bf16(ones, qx, PN0, 0, 0, 0); PN1 = __builtin_amdgcn_mfma_f32_32x32x16_bf16(ones, qx, PN1, 0, 0, 0); }
;     att_vfrag<GRP>(C, s & 1, vf);
; #pragma unroll
;     for (int j = (NE - 1) * 16 / NE; j < 16; ++j) ATT_SUMPACK(j);
;     ...
;     S.lrun += (ra + rb) + (rc + rd);
;     att_pv<GRP>(S, vf);
.Lmla_e_main:
	s_waitcnt lgkmcnt(5)
	v_mfma_f32_32x32x16_bf16 v[80:95], v[144:147], v[124:127], v[80:95]
	ds_read_b128 v[136:139], v174 offset:13408
	v_exp_f32_e32 v48, v48
	v_exp_f32_e32 v49, v49
	v_exp_f32_e32 v50, v50
	v_exp_f32_e32 v51, v51
	s_waitcnt lgkmcnt(5)
	v_mfma_f32_32x32x16_bf16 v[64:79], v[148:151], v[124:127], v[64:79]
	ds_read_b128 v[140:143], v174 offset:20064
	v_cvt_pk_bf16_f32 v216, v48, v49
	v_exp_f32_e32 v52, v52
	v_exp_f32_e32 v53, v53
	v_cvt_pk_bf16_f32 v217, v50, v51
	s_waitcnt lgkmcnt(5)
	v_mfma_f32_32x32x16_bf16 v[80:95], v[176:179], v[120:123], v[80:95]
	ds_read_b128 v[144:147], v174 offset:13440
	v_exp_f32_e32 v54, v54
	v_exp_f32_e32 v55, v55
	v_add_f32_e32 v248, v48, v52
	v_add_f32_e32 v249, v49, v53
	v_cvt_pk_bf16_f32 v218, v52, v53
	s_waitcnt lgkmcnt(5)
	v_mfma_f32_32x32x16_bf16 v[64:79], v[180:183], v[120:123], v[64:79]
	ds_read_b128 v[148:151], v174 offset:20096
	v_exp_f32_e32 v56, v56
	v_exp_f32_e32 v57, v57
	v_add_f32_e32 v250, v50, v54
	v_add_f32_e32 v251, v51, v55
	s_waitcnt lgkmcnt(3)
	v_mfma_f32_32x32x16_bf16 v[80:95], v[136:139], v[116:119], v[80:95]
	ds_read_b128 v[176:179], v174 offset:13472
	v_cvt_pk_bf16_f32 v219, v54, v55
	v_exp_f32_e32 v58, v58
	v_exp_f32_e32 v59, v59
	v_add_f32_e32 v248, v248, v56
	v_add_f32_e32 v249, v249, v57
	s_waitcnt lgkmcnt(3)
	v_mfma_f32_32x32x16_bf16 v[64:79], v[140:143], v[116:119], v[64:79]
	ds_read_b128 v[180:183], v174 offset:20128
	v_cvt_pk_bf16_f32 v220, v56, v57
	v_exp_f32_e32 v60, v60
	v_exp_f32_e32 v61, v61
	v_add_f32_e32 v250, v250, v58
	v_add_f32_e32 v251, v251, v59
	s_waitcnt lgkmcnt(3)
	v_mfma_f32_32x32x16_bf16 v[80:95], v[144:147], v[112:115], v[80:95]
	ds_read_b128 v[232:235], v157 offset:26624
	ds_read_b128 v[236:239], v157 offset:31232
	v_cvt_pk_bf16_f32 v221, v58, v59
	v_exp_f32_e32 v62, v62
	v_exp_f32_e32 v63, v63
	v_add_f32_e32 v248, v248, v60
	v_add_f32_e32 v249, v249, v61
	s_waitcnt lgkmcnt(4)
	v_mfma_f32_32x32x16_bf16 v[64:79], v[148:151], v[112:115], v[64:79]
	ds_read_b128 v[240:243], v157 offset:26656
	ds_read_b128 v[244:247], v157 offset:31264
	v_cvt_pk_bf16_f32 v222, v60, v61
	v_exp_f32_e32 v32, v32
	v_exp_f32_e32 v33, v33
	v_add_f32_e32 v250, v250, v62
	s_waitcnt lgkmcnt(5)
	v_mfma_f32_32x32x16_bf16 v[80:95], v[176:179], v[108:111], v[80:95]
	v_add_f32_e32 v251, v251, v63
	v_cvt_pk_bf16_f32 v223, v62, v63
	v_exp_f32_e32 v34, v34
	v_exp_f32_e32 v35, v35
	v_add_f32_e32 v248, v248, v32
	s_waitcnt lgkmcnt(4)
	v_mfma_f32_32x32x16_bf16 v[64:79], v[180:183], v[108:111], v[64:79]
	s_cmp_eq_u32 s72, 0
	v_xor_b32_e32 v195, 0x80000000, v175
	s_cbranch_scc1 .Lmla_e_norefnz
	s_mov_b32 s18, s16
	s_mov_b32 s19, s16
	s_mov_b32 s17, s16
	v_mov_b64_e32 v[186:187], s[18:19]
	v_mov_b64_e32 v[184:185], s[16:17]
	s_mov_b64 vcc, s[0:1]
	v_cndmask_b32_sdwa v96, v97, v195, vcc dst_sel:DWORD dst_unused:UNUSED_PAD src0_sel:DWORD src1_sel:WORD_1
	v_mov_b32_e32 v98, v97
	v_mov_b32_e32 v99, v97
	s_nop 1
	v_mfma_f32_32x32x16_bf16 v[80:95], v[184:187], v[96:99], v[80:95]
	v_mfma_f32_32x32x16_bf16 v[64:79], v[184:187], v[96:99], v[64:79]
.Lmla_e_norefnz:
	v_add_f32_e32 v249, v249, v33
	v_cvt_pk_bf16_f32 v224, v32, v33
	v_exp_f32_e32 v36, v36
	v_exp_f32_e32 v37, v37
	v_add_f32_e32 v250, v250, v34
	s_waitcnt lgkmcnt(3)
	v_mfma_f32_32x32x16_bf16 v[0:15], v[232:235], v[216:219], v[0:15]
	ds_read_b128 v[232:235], v157 offset:26688
	v_add_f32_e32 v251, v251, v35
	v_cvt_pk_bf16_f32 v225, v34, v35
	v_exp_f32_e32 v38, v38
	v_exp_f32_e32 v39, v39
	v_add_f32_e32 v248, v248, v36
	s_waitcnt lgkmcnt(3)
	v_mfma_f32_32x32x16_bf16 v[16:31], v[236:239], v[216:219], v[16:31]
	ds_read_b128 v[236:239], v157 offset:31296
	v_add_f32_e32 v249, v249, v37
	v_cvt_pk_bf16_f32 v226, v36, v37
	v_exp_f32_e32 v40, v40
	v_exp_f32_e32 v41, v41
	s_waitcnt lgkmcnt(3)
	v_mfma_f32_32x32x16_bf16 v[0:15], v[240:243], v[220:223], v[0:15]
	ds_read_b128 v[240:243], v157 offset:26720
	v_add_f32_e32 v250, v250, v38
	v_add_f32_e32 v251, v251, v39
	v_cvt_pk_bf16_f32 v227, v38, v39
	v_exp_f32_e32 v42, v42
	v_exp_f32_e32 v43, v43
	s_waitcnt lgkmcnt(3)
	v_mfma_f32_32x32x16_bf16 v[16:31], v[244:247], v[220:223], v[16:31]
	ds_read_b128 v[244:247], v157 offset:31328
	v_add_f32_e32 v248, v248, v40
	v_add_f32_e32 v249, v249, v41
	v_cvt_pk_bf16_f32 v228, v40, v41
	v_exp_f32_e32 v44, v44
	v_exp_f32_e32 v45, v45
	s_waitcnt lgkmcnt(3)
	v_mfma_f32_32x32x16_bf16 v[0:15], v[232:235], v[224:227], v[0:15]
	v_add_f32_e32 v250, v250, v42
	v_add_f32_e32 v251, v251, v43
	v_cvt_pk_bf16_f32 v229, v42, v43
	v_exp_f32_e32 v46, v46
	v_exp_f32_e32 v47, v47
	s_waitcnt lgkmcnt(2)
	v_mfma_f32_32x32x16_bf16 v[16:31], v[236:239], v[224:227], v[16:31]
	v_add_f32_e32 v248, v248, v44
	v_add_f32_e32 v249, v249, v45
	v_cvt_pk_bf16_f32 v230, v44, v45
	v_add_f32_e32 v250, v250, v46
	v_add_f32_e32 v251, v251, v47
	v_cvt_pk_bf16_f32 v231, v46, v47
	s_nop 1
	s_waitcnt lgkmcnt(1)
	v_mfma_f32_32x32x16_bf16 v[0:15], v[240:243], v[228:231], v[0:15]
	s_waitcnt lgkmcnt(0)
	v_mfma_f32_32x32x16_bf16 v[16:31], v[244:247], v[228:231], v[16:31]
	v_add_f32_e32 v248, v248, v249
	v_add_f32_e32 v250, v250, v251
	v_add_f32_e32 v248, v248, v250
	v_add_f32_e32 v170, v170, v248
	s_waitcnt lgkmcnt(0)
	s_barrier
	s_add_i32 s62, s69, 1
	s_lshr_b32 s71, s69, 6
	s_add_i32 s71, s71, s60
	s_and_b32 s10, s62, 63
	s_cmp_eq_u32 s10, 63
	s_cselect_b64 s[86:87], -1, 0
	s_cbranch_scc0 .Lmla_o_noq
	s_mul_i32 s18, s71, 0x60
	s_ashr_i32 s19, s18, 31
	v_lshl_add_u64 v[192:193], s[18:19], 1, v[164:165]
	global_load_dwordx4 v[128:131], v[192:193], off offset:192
	global_load_dwordx4 v[124:127], v[192:193], off offset:224
	global_load_dwordx4 v[120:123], v[192:193], off offset:256
	global_load_dwordx4 v[116:119], v[192:193], off offset:288
	global_load_dwordx4 v[112:115], v[192:193], off offset:320
	global_load_dwordx4 v[108:111], v[192:193], off offset:352
	s_waitcnt vmcnt(0)
; template <int GRP> __device__ __forceinline__ void att_stld(const AttCtx<GRP>& C, int s, u32x4& kreg, u32x4& preg, u32x4& vreg) {
;     constexpr int NSTEP = 256;
;     if (s + 2 < NSTEP) att_stk<GRP>(C, s & 1, kreg, preg);
;     if (s + 1 < NSTEP) att_stv<GRP>(C, (s + 1) & 1, vreg);
;     if (s + 3 < NSTEP) att_ldk<GRP>(C, s + 3, kreg, preg);
;     if (s + 2 < NSTEP) att_ldv<GRP>(C, s + 2, vreg);
; }
; template <int GRP, bool has_next> __device__ __forceinline__ void att_step(const AttCtx<GRP>& C, AttState<GRP>& S, int s, f32x16& P0, f32x16& P1, f32x16& PN0, f32x16& PN1, u32x4& kreg, u32x4& preg, u32x4& vreg) {
;     ...
;         att_kfrag<GRP, 0, NK0>(C, (s + 1) & 1, kfa);
;     }
;     if (has_next) { PN0 = __builtin_amdgcn_mfma_f32_32x32x16_bf16(kfa[0], S.qr[0], (f32x16){}, 0, 0, 0); PN1 = __builtin_amdgcn_mfma_f32_32x32x16_bf16(kfa[1], S.qr[0], (f32x16){}, 0, 0, 0); }
;     if ((t & 7) == 0) {
;         float ma = max3f(P0[0], P0[1], P0[2]), mb = max3f(P0[3], P0[4], P0[5]), mc = max3f(P1[0], P1[1], P1[2]), md = max3f(P1[3], P1[4], P1[5]);
;         ma = max3f(ma, P0[6], P0[7]); mb = max3f(mb, P0[8], P0[9]); mc = max3f(mc, P1[6], P1[7]); md = max3f(md, P1[8], P1[9]);
;         ma = max3f(ma, P0[10], P0[11]); mb = max3f(mb, P0[12], P0[13]); mc = max3f(mc, P1[10], P1[11]); md = max3f(md, P1[12], P1[13]);
;         ma = max3f(ma, P0[14], P0[15]); mc = max3f(mc, P1[14], P1[15]); ma = max3f(ma, mb, mc); mb = md;
;         const float mx = xhalf_max(max2f(ma, mb));
;         const int up = __any(mx > THR), dn = (t == 0) ? __any(mx < -THR) : 0;
;         if (up | dn) {
;             const float dl = ceilf((t == 0) ? mx : fmaxf(mx, 0.f));
;             const float f = (t == 0) ? 0.f : __builtin_amdgcn_exp2f(-dl);
;             S.mhat += dl; S.lrun *= f;
; #pragma unroll
;             for (int r = 0; r < 16; ++r) { P0[r] -= dl; P1[r] -= dl; S.o0[r] *= f; S.o1[r] *= f; }
;             S.refnz = __any(S.mhat != 0.f);
;         }
;     }
;     __builtin_amdgcn_sched_barrier(0);
;     const unsigned mbits = (t == 63 || C.hi != 0) ? 0u : (__float_as_uint(-S.mhat) >> 16);
;     const u32x4 qxw = {mbits, 0u, 0u, 0u}; const bf16x8 qx = __builtin_bit_cast(bf16x8, qxw);
;     const bf16x8 ones = {0x3f80, 0x3f80, 0x3f80, 0x3f80, 0x3f80, 0x3f80, 0x3f80, 0x3f80};
;     constexpr int NE = NKS - 1;
;     float ra = 0.f, rb = 0.f, rc = 0.f, rd = 0.f;
;     ...
; #pragma unroll
.Lmla_o_noq:
	ds_read_b128 v[136:139], v174 offset:0
	ds_read_b128 v[140:143], v174 offset:6656
	ds_read_b128 v[144:147], v174 offset:32
	ds_read_b128 v[148:151], v174 offset:6688
	s_waitcnt lgkmcnt(3)
	v_mfma_f32_32x32x16_bf16 v[48:63], v[136:139], v[128:131], 0
	ds_read_b128 v[176:179], v174 offset:64
	s_waitcnt lgkmcnt(3)
	v_mfma_f32_32x32x16_bf16 v[32:47], v[140:143], v[128:131], 0
	ds_read_b128 v[180:183], v174 offset:6720
	s_waitcnt vmcnt(1)
	ds_write_b128 v171, v[104:107] offset:13312
	s_and_saveexec_b64 s[82:83], s[6:7]
	ds_write_b128 v172, v[100:103] offset:13440
	s_or_b64 exec, exec, s[82:83]
	s_waitcnt vmcnt(0)
	ds_write_b128 v173, v[132:135] offset:26624
	s_cmpk_gt_u32 s62, 0xfc
	s_cbranch_scc1 .Lmla_o_nold
	s_mov_b32 s88, s70
	s_ashr_i32 s89, s70, 31
	v_lshl_add_u64 v[192:193], s[88:89], 1, v[158:159]
	s_and_b32 s14, s67, 0x1f000
	s_lshl_b32 s62, s14, 1
	global_load_dwordx4 v[104:107], v[192:193], off
	s_and_saveexec_b64 s[82:83], s[6:7]
	v_lshl_add_u64 v[190:191], v[160:161], 0, s[62:63]
	global_load_dwordx4 v[100:103], v[190:191], off
	s_or_b64 exec, exec, s[82:83]
.Lmla_o_nold:
	global_load_dwordx4 v[132:135], v[166:167], off
	s_waitcnt lgkmcnt(5)
	v_mfma_f32_32x32x16_bf16 v[48:63], v[144:147], v[124:127], v[48:63]
	ds_read_b128 v[136:139], v174 offset:96
	v_exp_f32_e32 v80, v80
	v_exp_f32_e32 v81, v81
	v_exp_f32_e32 v82, v82
	v_exp_f32_e32 v83, v83
	s_waitcnt lgkmcnt(5)
	v_mfma_f32_32x32x16_bf16 v[32:47], v[148:151], v[124:127], v[32:47]
	ds_read_b128 v[140:143], v174 offset:6752
	v_cvt_pk_bf16_f32 v216, v80, v81
	v_exp_f32_e32 v84, v84
	v_exp_f32_e32 v85, v85
	v_cvt_pk_bf16_f32 v217, v82, v83
	s_waitcnt lgkmcnt(5)
	v_mfma_f32_32x32x16_bf16 v[48:63], v[176:179], v[120:123], v[48:63]
	ds_read_b128 v[144:147], v174 offset:128
	v_exp_f32_e32 v86, v86
	v_exp_f32_e32 v87, v87
	v_add_f32_e32 v248, v80, v84
	v_add_f32_e32 v249, v81, v85
	v_cvt_pk_bf16_f32 v218, v84, v85
	s_waitcnt lgkmcnt(5)
	v_mfma_f32_32x32x16_bf16 v[32:47], v[180:183], v[120:123], v[32:47]
	ds_read_b128 v[148:151], v174 offset:6784
	v_exp_f32_e32 v88, v88
	v_exp_f32_e32 v89, v89
	v_add_f32_e32 v250, v82, v86
	v_add_f32_e32 v251, v83, v87
	s_waitcnt lgkmcnt(3)
	v_mfma_f32_32x32x16_bf16 v[48:63], v[136:139], v[116:119], v[48:63]
	ds_read_b128 v[176:179], v174 offset:160
	v_cvt_pk_bf16_f32 v219, v86, v87
	v_exp_f32_e32 v90, v90
	v_exp_f32_e32 v91, v91
	v_add_f32_e32 v248, v248, v88
	v_add_f32_e32 v249, v249, v89
	s_waitcnt lgkmcnt(3)
	v_mfma_f32_32x32x16_bf16 v[32:47], v[140:143], v[116:119], v[32:47]
	ds_read_b128 v[180:183], v174 offset:6816
	v_cvt_pk_bf16_f32 v220, v88, v89
	v_exp_f32_e32 v92, v92
	v_exp_f32_e32 v93, v93
	v_add_f32_e32 v250, v250, v90
	v_add_f32_e32 v251, v251, v91
	s_waitcnt lgkmcnt(3)
	v_mfma_f32_32x32x16_bf16 v[48:63], v[144:147], v[112:115], v[48:63]
	ds_read_b128 v[232:235], v157 offset:35840
	ds_read_b128 v[236:239], v157 offset:40448
	v_cvt_pk_bf16_f32 v221, v90, v91
	v_exp_f32_e32 v94, v94
	v_exp_f32_e32 v95, v95
	v_add_f32_e32 v248, v248, v92
	v_add_f32_e32 v249, v249, v93
	s_waitcnt lgkmcnt(4)
	v_mfma_f32_32x32x16_bf16 v[32:47], v[148:151], v[112:115], v[32:47]
	ds_read_b128 v[240:243], v157 offset:35872
	ds_read_b128 v[244:247], v157 offset:40480
	v_cvt_pk_bf16_f32 v222, v92, v93
	v_exp_f32_e32 v64, v64
	v_exp_f32_e32 v65, v65
	v_add_f32_e32 v250, v250, v94
	s_waitcnt lgkmcnt(5)
	v_mfma_f32_32x32x16_bf16 v[48:63], v[176:179], v[108:111], v[48:63]
	v_add_f32_e32 v251, v251, v95
	v_cvt_pk_bf16_f32 v223, v94, v95
	v_exp_f32_e32 v66, v66
	v_exp_f32_e32 v67, v67
	v_add_f32_e32 v248, v248, v64
	s_waitcnt lgkmcnt(4)
	v_mfma_f32_32x32x16_bf16 v[32:47], v[180:183], v[108:111], v[32:47]
	s_cmp_eq_u32 s72, 0
	s_cbranch_scc1 .Lmla_o_norefnz
	s_cmp_lg_u64 s[86:87], 0
	s_cbranch_scc1 .Lmla_o_norefnz
	s_mov_b32 s18, s16
	s_mov_b32 s19, s16
	s_mov_b32 s17, s16
	v_mov_b64_e32 v[186:187], s[18:19]
	v_mov_b64_e32 v[184:185], s[16:17]
	s_mov_b64 vcc, s[0:1]
	v_cndmask_b32_sdwa v96, v97, v195, vcc dst_sel:DWORD dst_unused:UNUSED_PAD src0_sel:DWORD src1_sel:WORD_1
	v_mov_b32_e32 v98, v97
	v_mov_b32_e32 v99, v97
	s_nop 1
	v_mfma_f32_32x32x16_bf16 v[48:63], v[184:187], v[96:99], v[48:63]
	v_mfma_f32_32x32x16_bf16 v[32:47], v[184:187], v[96:99], v[32:47]
.Lmla_o_norefnz:
	v_add_f32_e32 v249, v249, v65
	v_cvt_pk_bf16_f32 v224, v64, v65
	v_exp_f32_e32 v68, v68
	v_exp_f32_e32 v69, v69
	v_add_f32_e32 v250, v250, v66
	s_waitcnt lgkmcnt(3)
	v_mfma_f32_32x32x16_bf16 v[0:15], v[232:235], v[216:219], v[0:15]
	ds_read_b128 v[232:235], v157 offset:35904
	v_add_f32_e32 v251, v251, v67
	v_cvt_pk_bf16_f32 v225, v66, v67
	v_exp_f32_e32 v70, v70
	v_exp_f32_e32 v71, v71
	v_add_f32_e32 v248, v248, v68
	s_waitcnt lgkmcnt(3)
	v_mfma_f32_32x32x16_bf16 v[16:31], v[236:239], v[216:219], v[16:31]
	ds_read_b128 v[236:239], v157 offset:40512
	v_add_f32_e32 v249, v249, v69
	v_cvt_pk_bf16_f32 v226, v68, v69
	v_exp_f32_e32 v72, v72
	v_exp_f32_e32 v73, v73
	s_waitcnt lgkmcnt(3)
	v_mfma_f32_32x32x16_bf16 v[0:15], v[240:243], v[220:223], v[0:15]
	ds_read_b128 v[240:243], v157 offset:35936
	v_add_f32_e32 v250, v250, v70
	v_add_f32_e32 v251, v251, v71
	v_cvt_pk_bf16_f32 v227, v70, v71
	v_exp_f32_e32 v74, v74
	v_exp_f32_e32 v75, v75
	s_waitcnt lgkmcnt(3)
	v_mfma_f32_32x32x16_bf16 v[16:31], v[244:247], v[220:223], v[16:31]
	ds_read_b128 v[244:247], v157 offset:40544
	v_add_f32_e32 v248, v248, v72
	v_add_f32_e32 v249, v249, v73
	v_cvt_pk_bf16_f32 v228, v72, v73
	v_exp_f32_e32 v76, v76
	v_exp_f32_e32 v77, v77
	s_waitcnt lgkmcnt(3)
	v_mfma_f32_32x32x16_bf16 v[0:15], v[232:235], v[224:227], v[0:15]
	v_add_f32_e32 v250, v250, v74
	v_add_f32_e32 v251, v251, v75
	v_cvt_pk_bf16_f32 v229, v74, v75
	v_exp_f32_e32 v78, v78
	v_exp_f32_e32 v79, v79
	s_waitcnt lgkmcnt(2)
	v_mfma_f32_32x32x16_bf16 v[16:31], v[236:239], v[224:227], v[16:31]
	v_add_f32_e32 v248, v248, v76
	v_add_f32_e32 v249, v249, v77
	v_cvt_pk_bf16_f32 v230, v76, v77
	v_add_f32_e32 v250, v250, v78
	v_add_f32_e32 v251, v251, v79
	v_cvt_pk_bf16_f32 v231, v78, v79
	s_nop 1
	s_waitcnt lgkmcnt(1)
	v_mfma_f32_32x32x16_bf16 v[0:15], v[240:243], v[228:231], v[0:15]
	s_waitcnt lgkmcnt(0)
	v_mfma_f32_32x32x16_bf16 v[16:31], v[244:247], v[228:231], v[16:31]
	v_add_f32_e32 v248, v248, v249
	v_add_f32_e32 v250, v250, v251
	v_add_f32_e32 v248, v248, v250
	v_add_f32_e32 v170, v170, v248
	s_cmp_lg_u64 s[86:87], 0
	s_cbranch_scc0 .Lmla_o_nofin
; __device__ __forceinline__ unsigned cvtpk(float lo, float hi) { f32x2_t v = {lo, hi}; bf16x2_t b = __builtin_convertvector(v, bf16x2_t); return __builtin_bit_cast(unsigned, b); }
; __device__ __forceinline__ float xhalf_sum(float m) { auto rr = __builtin_amdgcn_permlane32_swap(__float_as_uint(m), __float_as_uint(m), false, false); return __uint_as_float(rr[0]) + __uint_as_float(rr[1]); }
; template <int GRP> __device__ __forceinline__ void att_finish_head(const AttCtx<GRP>& C, AttState<GRP>& S, int h) {
;     const float inv = 1.0f / xhalf_sum(S.lrun);
;     bf16_t* orow = C.O + C.qrow * 1024 + GRP * 512 + h * 64 + 4 * C.hi;
; #pragma unroll
;     for (int rr = 0; rr < 4; ++rr) {
;         const f32x4 v0 = (f32x4){S.o0[4 * rr], S.o0[4 * rr + 1], S.o0[4 * rr + 2], S.o0[4 * rr + 3]} * inv, v1 = (f32x4){S.o1[4 * rr], S.o1[4 * rr + 1], S.o1[4 * rr + 2], S.o1[4 * rr + 3]} * inv;
;         S.ssq += (v0[0] * v0[0] + v0[1] * v0[1]) + (v0[2] * v0[2] + v0[3] * v0[3]) + (v1[0] * v1[0] + v1[1] * v1[1]) + (v1[2] * v1[2] + v1[3] * v1[3]);
;         u32x2 s0, s1; s0.x = cvtpk(v0[0], v0[1]); s0.y = cvtpk(v0[2], v0[3]); s1.x = cvtpk(v1[0], v1[1]); s1.y = cvtpk(v1[2], v1[3]);
;         *(u32x2*)(orow + 8 * rr) = s0; *(u32x2*)(orow + 32 + 8 * rr) = s1;
;     }
; }
; template <int GRP, bool has_next> __device__ __forceinline__ void att_step(const AttCtx<GRP>& C, AttState<GRP>& S, int s, f32x16& P0, f32x16& P1, f32x16& PN0, f32x16& PN1, u32x4& kreg, u32x4& preg, u32x4& vreg) {
;     ...
;     if (t == 63) {
;         att_finish_head<GRP>(C, S, h);
;         S.o0 = (f32x16){}; S.o1 = (f32x16){}; S.lrun = 0.f; S.mhat = 0.f; S.refnz = 0;
;     }
	s_nop 7
	v_mov_b32_e32 v64, v170
	s_nop 1
	v_permlane32_swap_b32_e32 v170, v64
	v_add_f32_e32 v64, v170, v64
	v_div_scale_f32 v65, s[10:11], v64, v64, 1.0
	v_rcp_f32_e32 v66, v65
	s_lshl_b32 s10, s71, 6
	s_ashr_i32 s11, s10, 31
	v_mov_b32_e32 v175, 0
	v_fma_f32 v67, -v65, v66, 1.0
	v_fmac_f32_e32 v66, v67, v66
	v_div_scale_f32 v67, vcc, 1.0, v64, 1.0
	v_mul_f32_e32 v68, v67, v66
	v_fma_f32 v69, -v65, v68, v67
	v_fmac_f32_e32 v68, v69, v66
	v_fma_f32 v65, -v65, v68, v67
	v_div_fmas_f32 v65, v65, v66, v68
	v_div_fixup_f32 v64, v65, v64, 1.0
	v_pk_mul_f32 v[0:1], v[0:1], v[64:65] op_sel_hi:[1,0]
	v_pk_mul_f32 v[2:3], v[2:3], v[64:65] op_sel_hi:[1,0]
	v_pk_mul_f32 v[70:71], v[0:1], v[0:1]
	v_pk_mul_f32 v[68:69], v[2:3], v[2:3]
	v_pk_mul_f32 v[16:17], v[16:17], v[64:65] op_sel_hi:[1,0]
	v_pk_mul_f32 v[18:19], v[18:19], v[64:65] op_sel_hi:[1,0]
	v_pk_mov_b32 v[72:73], v[70:71], v[68:69] op_sel:[1,0]
	v_mov_b32_e32 v71, v69
	v_pk_add_f32 v[68:69], v[72:73], v[70:71]
	v_pk_mul_f32 v[70:71], v[18:19], v[18:19]
	v_pk_mul_f32 v[72:73], v[16:17], v[16:17]
	v_mov_b32_e32 v74, v70
	v_mov_b32_e32 v75, v72
	v_mov_b32_e32 v72, v71
	v_pk_add_f32 v[70:71], v[74:75], v[72:73]
	v_add_f32_e32 v65, v68, v69
	v_add_f32_e32 v65, v71, v65
	v_add_f32_e32 v65, v70, v65
	v_lshl_add_u64 v[66:67], s[10:11], 1, v[162:163]
	v_add_f32_e32 v65, v168, v65
	v_cvt_pk_bf16_f32 v0, v0, v1
	v_cvt_pk_bf16_f32 v1, v2, v3
	v_cvt_pk_bf16_f32 v2, v16, v17
	v_cvt_pk_bf16_f32 v3, v18, v19
	global_store_dwordx2 v[66:67], v[0:1], off
	global_store_dwordx2 v[66:67], v[2:3], off offset:64
	v_pk_mul_f32 v[0:1], v[4:5], v[64:65] op_sel_hi:[1,0]
	v_pk_mul_f32 v[2:3], v[6:7], v[64:65] op_sel_hi:[1,0]
	v_pk_mul_f32 v[4:5], v[20:21], v[64:65] op_sel_hi:[1,0]
	v_pk_mul_f32 v[6:7], v[22:23], v[64:65] op_sel_hi:[1,0]
	v_pk_mul_f32 v[16:17], v[2:3], v[2:3]
	v_pk_mul_f32 v[18:19], v[0:1], v[0:1]
	v_cvt_pk_bf16_f32 v0, v0, v1
	v_cvt_pk_bf16_f32 v1, v2, v3
	v_cvt_pk_bf16_f32 v2, v4, v5
	v_cvt_pk_bf16_f32 v3, v6, v7
	global_store_dwordx2 v[66:67], v[0:1], off offset:16
	global_store_dwordx2 v[66:67], v[2:3], off offset:80
	v_pk_mul_f32 v[2:3], v[8:9], v[64:65] op_sel_hi:[1,0]
	v_pk_mov_b32 v[20:21], v[18:19], v[16:17] op_sel:[1,0]
	v_mul_f32_e32 v8, v2, v2
	v_mov_b32_e32 v19, v17
	v_pk_mul_f32 v[0:1], v[10:11], v[64:65] op_sel_hi:[1,0]
	v_pk_fma_f32 v[8:9], v[2:3], v[2:3], v[8:9] op_sel_hi:[1,1,0]
	v_pk_add_f32 v[16:17], v[20:21], v[18:19]
	v_pk_mul_f32 v[18:19], v[6:7], v[6:7]
	v_pk_mul_f32 v[20:21], v[4:5], v[4:5]
	v_pk_mul_f32 v[4:5], v[26:27], v[64:65] op_sel_hi:[1,0]
	v_pk_mul_f32 v[6:7], v[24:25], v[64:65] op_sel_hi:[1,0]
	v_mul_f32_e32 v8, v0, v0
	v_pk_fma_f32 v[10:11], v[0:1], v[0:1], v[8:9] op_sel_hi:[1,1,0]
	v_cvt_pk_bf16_f32 v2, v2, v3
	v_cvt_pk_bf16_f32 v3, v0, v1
	v_cvt_pk_bf16_f32 v0, v6, v7
	v_cvt_pk_bf16_f32 v1, v4, v5
	v_mov_b32_e32 v22, v18
	v_mov_b32_e32 v23, v20
	v_mov_b32_e32 v20, v19
	global_store_dwordx2 v[66:67], v[2:3], off offset:32
	global_store_dwordx2 v[66:67], v[0:1], off offset:96
	v_pk_mul_f32 v[0:1], v[12:13], v[64:65] op_sel_hi:[1,0]
	v_pk_add_f32 v[18:19], v[22:23], v[20:21]
	v_pk_mul_f32 v[2:3], v[14:15], v[64:65] op_sel_hi:[1,0]
	v_mov_b32_e32 v21, v6
	v_mov_b32_e32 v6, v1
	v_mul_f32_e32 v8, v2, v2
	v_mul_f32_e32 v10, v3, v3
	v_mov_b32_e32 v20, v0
	v_pk_mul_f32 v[6:7], v[6:7], v[6:7]
	v_pk_add_f32 v[16:17], v[16:17], v[16:17] op_sel:[0,1] op_sel_hi:[1,0]
	v_pk_mul_f32 v[12:13], v[28:29], v[64:65] op_sel_hi:[1,0]
	v_pk_fma_f32 v[6:7], v[20:21], v[20:21], v[6:7]
	v_pk_add_f32 v[8:9], v[8:9], v[10:11]
	v_pk_add_f32 v[16:17], v[18:19], v[16:17] op_sel:[1,0] op_sel_hi:[0,1]
	v_pk_add_f32 v[6:7], v[6:7], v[8:9]
	v_mov_b32_e32 v9, v4
	v_mov_b32_e32 v4, v13
	v_pk_add_f32 v[16:17], v[18:19], v[16:17]
	v_pk_mul_f32 v[14:15], v[30:31], v[64:65] op_sel_hi:[1,0]
	v_mov_b32_e32 v8, v12
	v_pk_mul_f32 v[4:5], v[4:5], v[4:5]
	v_mul_f32_e32 v18, v14, v14
	v_mul_f32_e32 v64, v15, v15
	v_pk_fma_f32 v[4:5], v[8:9], v[8:9], v[4:5]
	v_mov_b32_e32 v19, v16
	v_pk_add_f32 v[4:5], v[4:5], v[6:7]
	v_pk_add_f32 v[6:7], v[18:19], v[64:65]
	v_cvt_pk_bf16_f32 v0, v0, v1
	v_pk_add_f32 v[4:5], v[4:5], v[6:7]
	v_cvt_pk_bf16_f32 v1, v2, v3
	v_cvt_pk_bf16_f32 v2, v12, v13
	v_cvt_pk_bf16_f32 v3, v14, v15
	v_add_f32_e32 v168, v4, v5
	global_store_dwordx2 v[66:67], v[0:1], off offset:48
	global_store_dwordx2 v[66:67], v[2:3], off offset:112
	s_mov_b32 s72, 0
	v_mov_b32_e32 v170, 0
	v_mov_b32_e32 v0, 0
	v_mov_b32_e32 v1, v175
	v_mov_b32_e32 v2, v175
	v_mov_b32_e32 v3, v175
	v_mov_b32_e32 v4, v175
	v_mov_b32_e32 v5, v175
	v_mov_b32_e32 v6, v175
	v_mov_b32_e32 v7, v175
	v_mov_b32_e32 v8, v175
	v_mov_b32_e32 v9, v175
	v_mov_b32_e32 v10, v175
	v_mov_b32_e32 v11, v175
	v_mov_b32_e32 v12, v175
	v_mov_b32_e32 v13, v175
	v_mov_b32_e32 v14, v175
	v_mov_b32_e32 v15, v175
	v_mov_b32_e32 v16, 0
	v_mov_b32_e32 v17, v175
	v_mov_b32_e32 v18, v175
	v_mov_b32_e32 v19, v175
	v_mov_b32_e32 v20, v175
	v_mov_b32_e32 v21, v175
	v_mov_b32_e32 v22, v175
	v_mov_b32_e32 v23, v175
	v_mov_b32_e32 v24, v175
	v_mov_b32_e32 v25, v175
	v_mov_b32_e32 v26, v175
	v_mov_b32_e32 v27, v175
	v_mov_b32_e32 v28, v175
	v_mov_b32_e32 v29, v175
	v_mov_b32_e32 v30, v175
	v_mov_b32_e32 v31, v175
